# mode-B attention: run-time Cauchy-Schwarz score bound from the QK-norm gains replaces running-max tracking (original loop kept as fallback)
# speedup vs baseline: 1.0209x; 1.0082x over previous
; DI void e1_chunk(const Params& p, int layer, int chunk) {
;     ...
;     const float* gain = (j < 4 ? p.b_q_gain : p.b_k_gain) + layer * 64;
;     const float post = j < 4 ? QSCALE64 : 1.f;
; template <int MODE>
; DI void attn_tile(const Params& p, int layer, int tile, char* smem) {
;     ...
;   f32x16 o0, o1, negm;
; #pragma unroll
;   for (int i = 0; i < 16; ++i) { o0[i] = 0.f; o1[i] = 0.f; negm[i] = 0.f; }
;   float mref = 0.f, lsum = 0.f;
;   bool started = false;
;   int qr = 0, qc = 0, cs = 0, rs = 0;
;   if (MODE == 2) { qr = qpos >> 6; qc = qpos & 63; cs = qc - 8; cs = cs < 0 ? 0 : (cs > 48 ? 48 : cs); rs = qr - 4; rs = rs < 0 ? 0 : (rs > 56 ? 56 : rs); }
;   const int i16 = lane & 15, qq = i16 >> 2, pp4 = i16 & 3, g16 = (lane >> 4) & 1;
.LBB0_131:
	v_readlane_b32 s0, v253, 38
	v_readlane_b32 s1, v253, 39
	v_readlane_b32 s4, v253, 40
	v_readlane_b32 s5, v253, 41
	v_readlane_b32 s6, v255, 46
	s_lshl_b32 s6, s6, 8
	s_add_u32 s0, s0, s6
	s_addc_u32 s1, s1, 0
	s_add_u32 s4, s4, s6
	s_addc_u32 s5, s5, 0
	v_lshlrev_b32_e32 v2, 2, v196
	global_load_dword v3, v2, s[0:1]
	global_load_dword v4, v2, s[4:5]
	s_waitcnt vmcnt(0)
	v_and_b32_e32 v3, 0x7fffffff, v3
	v_and_b32_e32 v4, 0x7fffffff, v4
	v_lshlrev_b32_e32 v5, 2, v252
	ds_bpermute_b32 v6, v5, v3
	ds_bpermute_b32 v7, v5, v4
	s_waitcnt lgkmcnt(0)
	v_max_f32_e32 v3, v3, v6
	v_max_f32_e32 v4, v4, v7
	v_lshlrev_b32_e32 v5, 2, v195
	ds_bpermute_b32 v6, v5, v3
	ds_bpermute_b32 v7, v5, v4
	s_waitcnt lgkmcnt(0)
	v_max_f32_e32 v3, v3, v6
	v_max_f32_e32 v4, v4, v7
	v_lshlrev_b32_e32 v5, 2, v198
	ds_bpermute_b32 v6, v5, v3
	ds_bpermute_b32 v7, v5, v4
	s_waitcnt lgkmcnt(0)
	v_max_f32_e32 v3, v3, v6
	v_max_f32_e32 v4, v4, v7
	v_lshlrev_b32_e32 v5, 2, v199
	ds_bpermute_b32 v6, v5, v3
	ds_bpermute_b32 v7, v5, v4
	s_waitcnt lgkmcnt(0)
	v_max_f32_e32 v3, v3, v6
	v_max_f32_e32 v4, v4, v7
	v_lshlrev_b32_e32 v5, 2, v200
	ds_bpermute_b32 v6, v5, v3
	ds_bpermute_b32 v7, v5, v4
	s_waitcnt lgkmcnt(0)
	v_max_f32_e32 v3, v3, v6
	v_max_f32_e32 v4, v4, v7
	v_lshlrev_b32_e32 v5, 2, v201
	ds_bpermute_b32 v6, v5, v3
	ds_bpermute_b32 v7, v5, v4
	s_waitcnt lgkmcnt(0)
	v_max_f32_e32 v3, v3, v6
	v_max_f32_e32 v4, v4, v7
	v_mul_f32_e32 v3, v3, v4
	v_mul_f32_e32 v3, 0xc13c0000, v3
	s_nop 1
	v_readfirstlane_b32 s84, v3
	s_nop 3
	s_cmp_le_u32 s84, 0xc2800000
	s_cselect_b32 s85, 1, 0
	s_cmp_ge_u32 s84, 0x80000000
	s_cselect_b32 s85, s85, 0
	v_readlane_b32 s26, v254, 15
	s_mov_b32 s16, 0
	v_readlane_b32 s20, v254, 9
	v_readlane_b32 s21, v254, 10
	v_readlane_b32 s22, v254, 11
	v_readlane_b32 s23, v254, 12
	v_readlane_b32 s24, v254, 13
	v_readlane_b32 s25, v254, 14
	v_readlane_b32 s27, v254, 16
	s_branch .LBB0_134

; template <int MODE>
; DI void attn_tile(const Params& p, int layer, int tile, char* smem) {
;     ...
;   f32x16 o0, o1, negm;
; #pragma unroll
;   for (int i = 0; i < 16; ++i) { o0[i] = 0.f; o1[i] = 0.f; negm[i] = 0.f; }
;   float mref = 0.f, lsum = 0.f;
;     ...
;   const int ntile = kt1 - kt0;
;   gload(rk1, rv1, kt0);
;   gload(rk0, rv0, kt0 + 1);
;   lstore(rk1, rv1, 0);
;   gload(rk1, rv1, kt0 + 2);
;   __syncthreads();
.LBB0_143:
	s_or_b64 exec, exec, s[0:1]
	v_add_u32_e32 v0, 0x4d000, v168
	v_lshl_add_u64 v[14:15], v[0:1], 1, s[12:13]
	v_add_u32_e32 v0, 0x4d000, v170
	v_lshl_add_u64 v[16:17], v[0:1], 1, s[14:15]
	global_load_dwordx4 v[126:129], v[14:15], off
	global_load_dwordx4 v[122:125], v[16:17], off
	v_mul_lo_u32 v9, v9, s87
	v_lshlrev_b32_e32 v0, 3, v7
	v_lshrrev_b32_e32 v11, 2, v8
	v_lshl_add_u32 v172, v164, 1, v9
	v_lshlrev_b32_e32 v171, 2, v7
	v_and_b32_e32 v169, 63, v8
	v_and_b32_e32 v8, 16, v8
	s_waitcnt vmcnt(4)
	ds_write_b128 v172, v[2:5] offset:26624
	v_mul_u32_u24_e32 v2, 0x48, v163
	v_and_or_b32 v3, v11, 3, v171
	v_and_b32_e32 v4, 24, v6
	v_lshlrev_b32_e32 v0, 1, v0
	v_lshl_or_b32 v4, v8, 1, v4
	v_mul_u32_u24_e32 v3, 0x48, v3
	v_lshl_add_u32 v174, v2, 1, v0
	v_lshlrev_b32_e32 v0, 1, v12
	v_mov_b32_e32 v14, v1
	v_mov_b32_e32 v15, v1
	v_lshl_add_u32 v173, v3, 1, v4
	v_lshl_add_u32 v175, v10, 1, v0
	v_mov_b32_e32 v0, v1
	v_mov_b32_e32 v2, v1
	v_mov_b32_e32 v3, v1
	v_mov_b32_e32 v4, v1
	v_mov_b32_e32 v5, v1
	v_mov_b32_e32 v6, v1
	v_mov_b32_e32 v7, v1
	v_mov_b32_e32 v8, v1
	v_mov_b32_e32 v9, v1
	v_mov_b32_e32 v10, v1
	v_mov_b32_e32 v11, v1
	v_mov_b32_e32 v12, v1
	v_mov_b32_e32 v13, v1
	v_mov_b64_e32 v[32:33], v[14:15]
	v_mov_b32_e32 v176, 0
	v_mov_b64_e32 v[30:31], v[12:13]
	v_mov_b64_e32 v[28:29], v[10:11]
	v_mov_b64_e32 v[26:27], v[8:9]
	v_mov_b64_e32 v[24:25], v[6:7]
	v_mov_b64_e32 v[22:23], v[4:5]
	v_mov_b64_e32 v[20:21], v[2:3]
	v_mov_b64_e32 v[18:19], v[0:1]
	v_mov_b64_e32 v[16:17], v[14:15]
	s_lshl_b32 s18, s17, 6
	v_mov_b32_e32 v177, 0
	s_mov_b32 s19, -2
	v_mov_b32_e32 v178, 0
	v_mov_b64_e32 v[14:15], v[12:13]
	v_mov_b64_e32 v[12:13], v[10:11]
	v_mov_b64_e32 v[10:11], v[8:9]
	v_mov_b64_e32 v[8:9], v[6:7]
	v_mov_b64_e32 v[6:7], v[4:5]
	v_mov_b64_e32 v[4:5], v[2:3]
	v_mov_b64_e32 v[2:3], v[0:1]
	v_mov_b32_e32 v34, 0
	v_mov_b32_e32 v35, v176
	v_mov_b32_e32 v36, v176
	v_mov_b32_e32 v37, v176
	v_mov_b32_e32 v38, v176
	v_mov_b32_e32 v39, v176
	v_mov_b32_e32 v40, v176
	v_mov_b32_e32 v41, v176
	v_mov_b32_e32 v42, v176
	v_mov_b32_e32 v43, v176
	v_mov_b32_e32 v44, v176
	v_mov_b32_e32 v45, v176
	v_mov_b32_e32 v46, v176
	v_mov_b32_e32 v47, v176
	v_mov_b32_e32 v48, v176
	v_mov_b32_e32 v49, v176
	s_cmp_eq_u32 s85, 0
	s_cbranch_scc1 .Lslow_b
	v_mov_b32_e32 v34, s84
	v_mov_b32_e32 v35, s84
	v_mov_b32_e32 v36, s84
	v_mov_b32_e32 v37, s84
	v_mov_b32_e32 v38, s84
	v_mov_b32_e32 v39, s84
	v_mov_b32_e32 v40, s84
	v_mov_b32_e32 v41, s84
	v_mov_b32_e32 v42, s84
	v_mov_b32_e32 v43, s84
	v_mov_b32_e32 v44, s84
	v_mov_b32_e32 v45, s84
	v_mov_b32_e32 v46, s84
	v_mov_b32_e32 v47, s84
	v_mov_b32_e32 v48, s84
	v_mov_b32_e32 v49, s84
	s_waitcnt lgkmcnt(0)
	s_barrier
	s_branch .Lfast_b
.Lslow_b:
	s_waitcnt lgkmcnt(0)
	s_barrier
	s_branch .LBB0_145

; DI unsigned pack2(float a, float b) { f32x2 v = {a, b}; bf16v2 r = __builtin_convertvector(v, bf16v2); return __builtin_bit_cast(unsigned, r); }
; DI f32x16 mfma(bf16x8 a, bf16x8 b, f32x16 c) { return __builtin_amdgcn_mfma_f32_32x32x16_bf16(a, b, c, 0, 0, 0); }
; DI float fexp2(float x) { return __builtin_amdgcn_exp2f(x); }
; template <int MODE>
; DI void attn_tile(const Params& p, int layer, int tile, char* smem) {
;     ...
;       float ps = 0.f;
; #pragma unroll
;       for (int i = 0; i < 16; ++i) { s0[i] = fexp2(s0[i]); s1[i] = fexp2(s1[i]); ps += s0[i] + s1[i]; }
;       lsum += ps;
; #pragma unroll
;       for (int c = 0; c < 2; ++c) {
; #pragma unroll
;         for (int s = 0; s < 2; ++s) {
;           u32x4 pw;
;           if (c == 0) pw = (u32x4){pack2(s0[8 * s], s0[8 * s + 1]), pack2(s0[8 * s + 2], s0[8 * s + 3]), pack2(s0[8 * s + 4], s0[8 * s + 5]), pack2(s0[8 * s + 6], s0[8 * s + 7])};
;           else pw = (u32x4){pack2(s1[8 * s], s1[8 * s + 1]), pack2(s1[8 * s + 2], s1[8 * s + 3]), pack2(s1[8 * s + 4], s1[8 * s + 5]), pack2(s1[8 * s + 6], s1[8 * s + 7])};
;           const bf16x8 pf = __builtin_bit_cast(bf16x8, pw);
;           o0 = mfma(vf[2 * (2 * c + s)], pf, o0);
;           o1 = mfma(vf[2 * (2 * c + s) + 1], pf, o1);
;         }
;       }
;     ...
;   for (int j = 0; j < ntile; j += 2) {
;     compute(0, kt0 + j);
;     lstore(rk0, rv0, 1);
;     gload(rk0, rv0, kt0 + j + 3);
;     __syncthreads();
;     if (j + 1 >= ntile) break;
;     compute(1, kt0 + j + 1);
;     lstore(rk1, rv1, 0);
;     gload(rk1, rv1, kt0 + j + 4);
;     __syncthreads();
.Lstf_b_s1skip:
	s_or_b64 exec, exec, s[0:1]
	s_add_i32 s19, s19, 2
	s_min_u32 s0, s19, 60
	s_mul_i32 s0, s0, 0x4d000
	s_add_i32 s0, s0, 0xe7000
	s_waitcnt vmcnt(2)
	ds_write_b128 v172, v[114:117] offset:35840
	v_lshl_add_u32 v246, v168, 1, s0
	v_lshl_add_u32 v248, v170, 1, s0
	global_load_dwordx4 v[118:121], v246, s[12:13]
	global_load_dwordx4 v[114:117], v248, s[14:15]
	s_cmp_eq_u32 s32, 0
	s_cbranch_scc1 .Lstf_b_r1
	s_waitcnt lgkmcnt(0)
	s_barrier
.Lstf_b_r1:
	v_exp_f32_e32 v66, v66
	v_exp_f32_e32 v67, v67
	v_exp_f32_e32 v179, v68
	v_exp_f32_e32 v180, v69
	v_exp_f32_e32 v182, v70
	v_exp_f32_e32 v183, v71
	v_exp_f32_e32 v186, v72
	v_exp_f32_e32 v210, v73
	v_cvt_pk_bf16_f32 v68, v66, v67
	v_cvt_pk_bf16_f32 v69, v179, v180
	v_cvt_pk_bf16_f32 v70, v182, v183
	v_cvt_pk_bf16_f32 v71, v186, v210
	v_exp_f32_e32 v181, v85
	v_exp_f32_e32 v184, v86
	v_mfma_f32_32x32x16_bf16 v[18:33], v[158:161], v[68:71], v[18:33]
	v_exp_f32_e32 v211, v89
	v_exp_f32_e32 v188, v74
	v_exp_f32_e32 v191, v90
	v_exp_f32_e32 v189, v75
	v_exp_f32_e32 v192, v91
	v_exp_f32_e32 v190, v76
	v_exp_f32_e32 v89, v77
	v_mfma_f32_32x32x16_bf16 v[2:17], v[154:157], v[68:71], v[2:17]
	v_exp_f32_e32 v90, v78
	v_exp_f32_e32 v91, v79
	v_exp_f32_e32 v85, v80
	v_exp_f32_e32 v86, v81
	v_cvt_pk_bf16_f32 v68, v188, v189
	v_cvt_pk_bf16_f32 v69, v190, v89
	v_cvt_pk_bf16_f32 v70, v90, v91
	v_cvt_pk_bf16_f32 v71, v85, v86
	v_exp_f32_e32 v82, v82
	v_exp_f32_e32 v83, v83
	s_waitcnt lgkmcnt(10)
	v_mfma_f32_32x32x16_bf16 v[18:33], v[150:153], v[68:71], v[18:33]
	v_exp_f32_e32 v84, v84
	v_exp_f32_e32 v185, v87
	v_exp_f32_e32 v187, v88
	v_exp_f32_e32 v193, v92
	v_exp_f32_e32 v92, v93
	v_exp_f32_e32 v93, v94
	v_exp_f32_e32 v94, v95
	s_waitcnt lgkmcnt(8)
	v_mfma_f32_32x32x16_bf16 v[2:17], v[146:149], v[68:71], v[2:17]
	v_cvt_pk_bf16_f32 v68, v82, v83
	v_cvt_pk_bf16_f32 v69, v84, v181
	v_cvt_pk_bf16_f32 v70, v184, v185
	v_cvt_pk_bf16_f32 v71, v187, v211
	v_exp_f32_e32 v87, v96
	v_exp_f32_e32 v88, v97
	s_waitcnt lgkmcnt(6)
	v_mfma_f32_32x32x16_bf16 v[18:33], v[142:145], v[68:71], v[18:33]
	s_waitcnt lgkmcnt(4)
	v_mfma_f32_32x32x16_bf16 v[2:17], v[138:141], v[68:71], v[2:17]
	v_cvt_pk_bf16_f32 v68, v191, v192
	v_cvt_pk_bf16_f32 v69, v193, v92
	v_cvt_pk_bf16_f32 v70, v93, v94
	v_cvt_pk_bf16_f32 v71, v87, v88
	s_waitcnt lgkmcnt(2)
	s_nop 0
	v_mfma_f32_32x32x16_bf16 v[18:33], v[130:133], v[68:71], v[18:33]
	s_waitcnt lgkmcnt(0)
	v_mfma_f32_32x32x16_bf16 v[2:17], v[134:137], v[68:71], v[2:17]
	s_cmp_lg_u32 s32, 0
	s_cbranch_scc1 .Lstf_b_n1
	s_barrier
.Lstf_b_n1:
	ds_read_b128 v[130:133], v174 offset:9216
	ds_read_b128 v[134:137], v174 offset:13824
	ds_read_b128 v[138:141], v174 offset:9248
	v_add_f32_e32 v0, v82, v66
	v_add_f32_e32 v82, v83, v67
	s_waitcnt lgkmcnt(2)
	v_mfma_f32_32x32x16_bf16 v[66:81], v[130:133], v[98:101], v[34:49]
	ds_read_b128 v[130:133], v174 offset:13856
	v_add_f32_e32 v0, 0, v0
	v_add_f32_e32 v0, v82, v0
	v_add_f32_e32 v82, v84, v179
	v_add_f32_e32 v0, v82, v0
	v_add_f32_e32 v82, v181, v180
	v_add_f32_e32 v0, v82, v0
	s_waitcnt lgkmcnt(2)
	v_mfma_f32_32x32x16_bf16 v[50:65], v[134:137], v[98:101], v[34:49]
	v_add_f32_e32 v82, v184, v182
	v_add_f32_e32 v0, v82, v0
	v_add_f32_e32 v82, v185, v183
	v_add_f32_e32 v0, v82, v0
	v_add_f32_e32 v82, v187, v186
	ds_read_b128 v[134:137], v174 offset:9280
	v_add_f32_e32 v0, v82, v0
	v_add_f32_e32 v82, v211, v210
	s_waitcnt lgkmcnt(2)
	v_mfma_f32_32x32x16_bf16 v[66:81], v[138:141], v[102:105], v[66:81]
	v_add_f32_e32 v0, v82, v0
	v_add_f32_e32 v82, v191, v188
	v_add_f32_e32 v0, v82, v0
	v_add_f32_e32 v82, v192, v189
	v_add_f32_e32 v0, v82, v0
	v_add_f32_e32 v82, v193, v190
	v_add_f32_e32 v0, v82, v0
	s_waitcnt lgkmcnt(1)
	v_mfma_f32_32x32x16_bf16 v[50:65], v[130:133], v[102:105], v[50:65]
	v_add_f32_e32 v82, v92, v89
	v_add_f32_e32 v0, v82, v0
	v_add_f32_e32 v82, v93, v90
	v_add_f32_e32 v0, v82, v0
	v_add_f32_e32 v82, v94, v91
	ds_read_b128 v[90:93], v174 offset:13888
	ds_read_b128 v[94:97], v174 offset:9312
	ds_read_b128 v[146:149], v174 offset:13920
	s_waitcnt lgkmcnt(3)
	v_mfma_f32_32x32x16_bf16 v[66:81], v[134:137], v[106:109], v[66:81]
	v_add_f32_e32 v0, v82, v0
	v_add_f32_e32 v82, v87, v85
	v_add_f32_e32 v0, v82, v0
	v_add_f32_e32 v82, v88, v86
	v_add_f32_e32 v0, v82, v0
	ds_read_b64_tr_b16 v[142:143], v173 offset:35840
	ds_read_b64_tr_b16 v[144:145], v173 offset:36992
	ds_read_b64_tr_b16 v[140:141], v173 offset:37056
	ds_read_b64_tr_b16 v[138:139], v173 offset:35904
	ds_read_b64_tr_b16 v[134:135], v173 offset:38144
	ds_read_b64_tr_b16 v[136:137], v173 offset:39296
	ds_read_b64_tr_b16 v[132:133], v173 offset:39360
	ds_read_b64_tr_b16 v[130:131], v173 offset:38208
	v_add_f32_e32 v0, v178, v0
	s_waitcnt lgkmcnt(10)
	v_mfma_f32_32x32x16_bf16 v[50:65], v[90:93], v[106:109], v[50:65]
	s_waitcnt lgkmcnt(9)
	v_mfma_f32_32x32x16_bf16 v[66:81], v[94:97], v[110:113], v[66:81]
	ds_read_b64_tr_b16 v[94:95], v173 offset:40448
	ds_read_b64_tr_b16 v[96:97], v173 offset:41600
	ds_read_b64_tr_b16 v[92:93], v173 offset:41664
	ds_read_b64_tr_b16 v[90:91], v173 offset:40512
	ds_read_b64_tr_b16 v[82:83], v173 offset:42752
	ds_read_b64_tr_b16 v[84:85], v173 offset:43904
	ds_read_b64_tr_b16 v[88:89], v173 offset:43968
	ds_read_b64_tr_b16 v[86:87], v173 offset:42816
	s_waitcnt lgkmcnt(14)
	v_mfma_f32_32x32x16_bf16 v[50:65], v[146:149], v[110:113], v[50:65]
	s_and_saveexec_b64 s[0:1], s[6:7]
	s_cbranch_execz .Lstf_b_s0skip
	s_waitcnt vmcnt(3)
	ds_write_b128 v175, v[126:129]
; DI unsigned pack2(float a, float b) { f32x2 v = {a, b}; bf16v2 r = __builtin_convertvector(v, bf16v2); return __builtin_bit_cast(unsigned, r); }
; DI f32x16 mfma(bf16x8 a, bf16x8 b, f32x16 c) { return __builtin_amdgcn_mfma_f32_32x32x16_bf16(a, b, c, 0, 0, 0); }
; DI float fexp2(float x) { return __builtin_amdgcn_exp2f(x); }
; template <int MODE>
; DI void attn_tile(const Params& p, int layer, int tile, char* smem) {
;     ...
;       float ps = 0.f;
; #pragma unroll
;       for (int i = 0; i < 16; ++i) { s0[i] = fexp2(s0[i]); s1[i] = fexp2(s1[i]); ps += s0[i] + s1[i]; }
;       lsum += ps;
; #pragma unroll
;       for (int c = 0; c < 2; ++c) {
; #pragma unroll
;         for (int s = 0; s < 2; ++s) {
;           u32x4 pw;
;           if (c == 0) pw = (u32x4){pack2(s0[8 * s], s0[8 * s + 1]), pack2(s0[8 * s + 2], s0[8 * s + 3]), pack2(s0[8 * s + 4], s0[8 * s + 5]), pack2(s0[8 * s + 6], s0[8 * s + 7])};
;           else pw = (u32x4){pack2(s1[8 * s], s1[8 * s + 1]), pack2(s1[8 * s + 2], s1[8 * s + 3]), pack2(s1[8 * s + 4], s1[8 * s + 5]), pack2(s1[8 * s + 6], s1[8 * s + 7])};
;           const bf16x8 pf = __builtin_bit_cast(bf16x8, pw);
;           o0 = mfma(vf[2 * (2 * c + s)], pf, o0);
;           o1 = mfma(vf[2 * (2 * c + s) + 1], pf, o1);
;         }
;       }
;     ...
;     if (j + 1 >= ntile) break;
;     compute(1, kt0 + j + 1);
;     lstore(rk1, rv1, 0);
;     gload(rk1, rv1, kt0 + j + 4);
;     __syncthreads();
;   }
.Lstf_b_s0skip:
	s_or_b64 exec, exec, s[0:1]
	s_min_u32 s0, s19, 59
	s_mul_i32 s0, s0, 0x4d000
	s_add_i32 s0, s0, 0x134000
	v_lshl_add_u32 v246, v168, 1, s0
	v_lshl_add_u32 v248, v170, 1, s0
	global_load_dwordx4 v[126:129], v246, s[12:13]
	s_waitcnt vmcnt(3)
	ds_write_b128 v172, v[122:125] offset:26624
	global_load_dwordx4 v[122:125], v248, s[14:15]
	s_cmp_eq_u32 s32, 0
	s_cbranch_scc1 .Lstf_b_r0
	s_waitcnt lgkmcnt(0)
	s_barrier
.Lstf_b_r0:
	v_exp_f32_e32 v66, v66
	v_exp_f32_e32 v67, v67
	v_exp_f32_e32 v68, v68
	v_exp_f32_e32 v69, v69
	v_exp_f32_e32 v70, v70
	v_exp_f32_e32 v71, v71
	v_exp_f32_e32 v72, v72
	v_exp_f32_e32 v73, v73
	v_cvt_pk_bf16_f32 v148, v66, v67
	v_cvt_pk_bf16_f32 v149, v68, v69
	v_cvt_pk_bf16_f32 v150, v70, v71
	v_cvt_pk_bf16_f32 v151, v72, v73
	v_exp_f32_e32 v146, v57
	v_exp_f32_e32 v57, v74
	v_mfma_f32_32x32x16_bf16 v[18:33], v[142:145], v[148:151], v[18:33]
	v_exp_f32_e32 v74, v58
	v_exp_f32_e32 v58, v75
	v_exp_f32_e32 v75, v59
	v_exp_f32_e32 v59, v76
	v_exp_f32_e32 v76, v60
	v_exp_f32_e32 v60, v77
	v_exp_f32_e32 v77, v61
	s_waitcnt lgkmcnt(12)
	v_mfma_f32_32x32x16_bf16 v[2:17], v[138:141], v[148:151], v[2:17]
	v_exp_f32_e32 v61, v78
	v_exp_f32_e32 v78, v62
	v_exp_f32_e32 v62, v79
	v_exp_f32_e32 v79, v63
	v_exp_f32_e32 v63, v80
	v_exp_f32_e32 v80, v64
	v_exp_f32_e32 v64, v81
	v_cvt_pk_bf16_f32 v138, v57, v58
	v_cvt_pk_bf16_f32 v139, v59, v60
	v_cvt_pk_bf16_f32 v140, v61, v62
	v_cvt_pk_bf16_f32 v141, v63, v64
	v_exp_f32_e32 v50, v50
	v_exp_f32_e32 v51, v51
	s_waitcnt lgkmcnt(10)
	v_mfma_f32_32x32x16_bf16 v[18:33], v[134:137], v[138:141], v[18:33]
	v_exp_f32_e32 v52, v52
	v_exp_f32_e32 v53, v53
	v_exp_f32_e32 v54, v54
	v_exp_f32_e32 v55, v55
	v_exp_f32_e32 v56, v56
	v_exp_f32_e32 v65, v65
	s_waitcnt lgkmcnt(8)
	v_mfma_f32_32x32x16_bf16 v[2:17], v[130:133], v[138:141], v[2:17]
	v_cvt_pk_bf16_f32 v130, v50, v51
	v_cvt_pk_bf16_f32 v131, v52, v53
	v_cvt_pk_bf16_f32 v132, v54, v55
	v_cvt_pk_bf16_f32 v133, v56, v146
	s_waitcnt lgkmcnt(6)
	s_nop 0
	v_mfma_f32_32x32x16_bf16 v[18:33], v[94:97], v[130:133], v[18:33]
	s_waitcnt lgkmcnt(4)
	v_mfma_f32_32x32x16_bf16 v[2:17], v[90:93], v[130:133], v[2:17]
	v_cvt_pk_bf16_f32 v90, v74, v75
	v_cvt_pk_bf16_f32 v91, v76, v77
	v_cvt_pk_bf16_f32 v92, v78, v79
	v_cvt_pk_bf16_f32 v93, v80, v65
	s_waitcnt lgkmcnt(2)
	s_nop 0
	v_mfma_f32_32x32x16_bf16 v[18:33], v[82:85], v[90:93], v[18:33]
	s_waitcnt lgkmcnt(0)
	v_mfma_f32_32x32x16_bf16 v[2:17], v[86:89], v[90:93], v[2:17]
	v_add_f32_e32 v50, v50, v66
	v_add_f32_e32 v50, 0, v50
	v_add_f32_e32 v51, v51, v67
	v_add_f32_e32 v50, v51, v50
	v_add_f32_e32 v51, v52, v68
	v_add_f32_e32 v50, v51, v50
	v_add_f32_e32 v51, v53, v69
	v_add_f32_e32 v50, v51, v50
	v_add_f32_e32 v51, v54, v70
	v_add_f32_e32 v50, v51, v50
	v_add_f32_e32 v51, v55, v71
	v_add_f32_e32 v50, v51, v50
	v_add_f32_e32 v51, v56, v72
	v_add_f32_e32 v50, v51, v50
	v_add_f32_e32 v51, v146, v73
	v_add_f32_e32 v50, v51, v50
	v_add_f32_e32 v51, v74, v57
	v_add_f32_e32 v50, v51, v50
	v_add_f32_e32 v51, v75, v58
	v_add_f32_e32 v50, v51, v50
	v_add_f32_e32 v51, v76, v59
	v_add_f32_e32 v50, v51, v50
	v_add_f32_e32 v51, v77, v60
	v_add_f32_e32 v50, v51, v50
	v_add_f32_e32 v51, v78, v61
	v_add_f32_e32 v50, v51, v50
	v_add_f32_e32 v51, v79, v62
	v_add_f32_e32 v50, v51, v50
	v_add_f32_e32 v51, v80, v63
	v_add_f32_e32 v50, v51, v50
	v_add_f32_e32 v51, v65, v64
	v_add_f32_e32 v50, v51, v50
	v_add_f32_e32 v178, v0, v50
	s_cmp_lg_u32 s32, 0
	s_cbranch_scc1 .Lstf_b_n0
	s_barrier
.Lstf_b_n0:
	s_cmp_lt_u32 s19, 62
	s_cbranch_scc1 .Lfast_b
	s_branch .LBB0_154
